# static s_setprio 1 for the late half (waves 4-7) during the FoX prompt trip loop, no per-segment flips
# baseline (speedup 1.0000x reference)
; #define LAS __attribute__((address_space(3)))
; __device__ __forceinline__ unsigned cvtpk(float lo, float hi) { f32x2 v = {lo, hi}; bf16x2_t b = __builtin_convertvector(v, bf16x2_t); return __builtin_bit_cast(unsigned, b); }
; __device__ __forceinline__ void prompt_unit_fox(const Args& a, int l, int b, int h, int qb, LAS unsigned char* lds) {
;     int tid_ = threadIdx.x; asm volatile("" : "+v"(tid_));
;     const int tid = tid_, lane = tid & 63, r32 = lane & 31, hi = lane >> 5, wid = __builtin_amdgcn_readfirstlane(tid >> 6);
;     const int q0 = qb * 256, NP = (q0 + 256) / 128, jd = q0 / 64 + (wid >> 1), jpd = jd >> 1;
;     const bool lateB = wid >= 4;
;     const int col = h * HD;
;     const size_t rowb = (size_t)b * T;
;     const bf16* Kh = (const bf16*)(a.ws + WS_K) + rowb * D + col; const bf16* Vh = (const bf16*)(a.ws + WS_V) + rowb * D + col;
;     const unsigned lds0 = (unsigned)(uintptr_t)lds;
;     const bf16* ksrc = Kh + (size_t)lane * D + wid * 8;
;     const bf16* vsrc = Vh + (size_t)(16 * (wid & 3) + (lane >> 2)) * D + (wid >> 2) * 32 + (lane & 3) * 8;
;     ...
;     ATT_DMA2(NP - 1, 0);
;     { const int idx = tid * 4; if (idx < q0 + 256) { const f32x4 c = *(const f32x4*)((const float*)(a.ws + WS_CKP) + (size_t)(b * 8 + h) * T + idx); *(LAS f32x4*)(lds + F_CK + idx * 4) = c;
; #pragma unroll
;         for (int e = 0; e < 4; ++e) { const float h1 = bf_hi_part(c[e]), r1 = c[e] - h1, h2 = bf_hi_part(r1), r2 = r1 - h2; ((LAS u32x2*)(lds + F_AUG))[idx + e] = (u32x2){cvtpk(h1, h2), cvtpk(r2, -1.0f)}; } } }
;     bf16x8 qr[4];
;     { const bf16* Qw = (const bf16*)(a.ws + WS_Q) + (rowb + q0 + wid * 32 + r32) * D + col;
; #pragma unroll
;       for (int d0 = 0; d0 < 4; ++d0) qr[d0] = *(const bf16x8*)(Qw + d0 * 16 + hi * 8); }
;     const lds_cptr vp0 = (lds_cptr)lds + F_V + ((lane >> 4) & 1) * 32 + (lane & 3) * 8 + (4 * hi + ((lane & 15) >> 2)) * 64;
;     const int ql = 32 * (wid & 1) + r32, qlim = ql + 1;
;     LAS float* wsf = (LAS float*)(lds + F_WSF) + wid * 64;
;     FoxState st; st.m = 0.f; st.l = 0.f; st.mq = (bf16x8){}; st.o[0] = (f32x16){}; st.o[1] = (f32x16){};
;     PairP pp; bool pending = false;
; #pragma unroll
;     for (int i = 0; i < 8; ++i) pp.w[i] = (u32x4){0u, 0u, 0u, 0u};
;     { ConvRegs cv; conv_load(cv, a, rowb + q0 + wid * 32, col, lane); conv_store<0>(cv, a, l, h, rowb + q0 + wid * 32, lane); }
.LBB0_311:
	s_or_b64 exec, exec, s[0:1]
	s_lshl_b32 s0, s6, 2
	s_ashr_i32 s1, s3, 7
	s_add_i32 s1, s1, s0
	s_ashr_i32 s89, s1, 1
	s_cmp_lt_i32 s77, 4
	s_cselect_b64 s[92:93], -1, 0
	s_cbranch_scc1 .Lnoprio_l0
	s_setprio 1
.Lnoprio_l0:
	s_lshl_b32 s0, s5, 11
	s_lshl_b32 s5, s77, 5
	s_or_b32 s0, s7, s0
	s_ashr_i32 s1, s5, 31
	s_add_u32 s91, s5, s0
	v_and_b32_e32 v175, 31, v19
	s_addc_u32 s0, s1, 0
	v_or_b32_e32 v168, s91, v175
	v_mov_b32_e32 v169, s0
	v_lshrrev_b32_e32 v1, 3, v20
	v_lshlrev_b64 v[2:3], 11, v[168:169]
	v_or_b32_e32 v168, s91, v1
	v_lshlrev_b32_e32 v4, 3, v20
	v_lshlrev_b64 v[170:171], 11, v[168:169]
	s_lshl_b32 s74, s4, 1
	s_mov_b32 s75, s87
	v_and_b32_e32 v174, 56, v4
	v_lshl_add_u64 v[8:9], s[94:95], 0, v[170:171]
	v_lshl_add_u64 v[8:9], v[8:9], 0, s[74:75]
	v_mov_b32_e32 v4, v174
	v_readlane_b32 s6, v242, 20
	v_lshl_add_u64 v[8:9], v[8:9], 0, v[4:5]
	v_readlane_b32 s7, v242, 21
	global_load_dwordx2 v[24:25], v[8:9], off offset:64
	global_load_dwordx2 v[22:23], v[8:9], off
	v_or_b32_e32 v58, 0x4000, v170
	v_lshl_add_u64 v[8:9], s[6:7], 0, v[170:171]
	v_lshl_add_u64 v[8:9], v[8:9], 0, s[74:75]
	v_lshl_add_u64 v[8:9], v[8:9], 0, v[4:5]
	v_mov_b32_e32 v59, v171
	global_load_dwordx2 v[28:29], v[8:9], off offset:64
	global_load_dwordx2 v[26:27], v[8:9], off
	v_lshl_add_u64 v[8:9], s[94:95], 0, v[58:59]
	v_lshl_add_u64 v[8:9], v[8:9], 0, s[74:75]
	v_lshl_add_u64 v[8:9], v[8:9], 0, v[4:5]
	global_load_dwordx2 v[32:33], v[8:9], off offset:64
	global_load_dwordx2 v[30:31], v[8:9], off
	v_lshl_add_u64 v[8:9], s[6:7], 0, v[58:59]
	v_lshrrev_b32_e32 v21, 5, v20
	v_lshl_add_u64 v[8:9], v[8:9], 0, s[74:75]
	v_lshlrev_b32_e32 v7, 1, v19
	v_lshrrev_b32_e32 v10, 2, v19
	v_lshlrev_b32_e32 v66, 2, v21
	v_lshl_add_u64 v[8:9], v[8:9], 0, v[4:5]
	v_and_b32_e32 v7, 32, v7
	global_load_dwordx2 v[36:37], v[8:9], off offset:64
	global_load_dwordx2 v[34:35], v[8:9], off
	v_and_or_b32 v8, v10, 3, v66
	v_add_u32_e32 v7, 0, v7
	v_lshlrev_b32_e32 v8, 6, v8
	v_or_b32_e32 v60, 0x8000, v170
	v_mov_b32_e32 v61, v171
	v_add3_u32 v180, v7, v6, v8
	v_lshl_add_u64 v[6:7], s[94:95], 0, v[60:61]
	v_and_or_b32 v67, s5, 32, v175
	s_and_b32 s5, s3, 0x3fffffc0
	v_lshl_add_u64 v[6:7], v[6:7], 0, s[74:75]
	v_writelane_b32 v237, s0, 11
	s_lshl_b32 s0, s4, 2
	s_lshl_b32 s4, s5, 2
	v_lshl_add_u64 v[6:7], v[6:7], 0, v[4:5]
	v_lshl_add_u64 v[10:11], s[6:7], 0, v[60:61]
	s_add_i32 s78, s4, 0
	v_readlane_b32 s4, v242, 22
	global_load_dwordx2 v[40:41], v[6:7], off offset:64
	global_load_dwordx2 v[38:39], v[6:7], off
	v_lshl_add_u64 v[10:11], v[10:11], 0, s[74:75]
	v_readlane_b32 s5, v242, 23
	v_lshl_add_u64 v[10:11], v[10:11], 0, v[4:5]
	v_readlane_b32 s8, v242, 45
	v_lshl_add_u64 v[2:3], s[4:5], 0, v[2:3]
	v_readlane_b32 s4, v242, 43
	global_load_dwordx2 v[44:45], v[10:11], off offset:64
	global_load_dwordx2 v[42:43], v[10:11], off
	v_mov_b32_e32 v173, v5
	v_lshlrev_b32_e32 v172, 4, v21
	v_lshl_add_u64 v[2:3], v[2:3], 0, s[74:75]
	v_or_b32_e32 v62, 0xc000, v170
	v_mov_b32_e32 v63, v171
	v_readlane_b32 s5, v242, 44
	v_readlane_b32 s9, v242, 46
	s_mov_b32 s1, s87
	v_lshl_add_u64 v[6:7], s[4:5], 0, v[170:171]
	v_lshl_add_u64 v[8:9], s[8:9], 0, v[170:171]
	v_lshl_add_u64 v[2:3], v[2:3], 0, v[172:173]
	v_lshl_add_u64 v[46:47], s[94:95], 0, v[62:63]
	v_lshl_add_u64 v[48:49], s[6:7], 0, v[62:63]
	v_lshl_add_u64 v[54:55], v[6:7], 0, s[0:1]
	v_lshl_add_u64 v[56:57], v[8:9], 0, s[0:1]
	global_load_dwordx4 v[6:9], v[2:3], off
	global_load_dwordx4 v[10:13], v[2:3], off offset:32
	global_load_dwordx4 v[14:17], v[2:3], off offset:64
	global_load_dwordx4 v[116:119], v[2:3], off offset:96
	v_lshl_add_u64 v[2:3], v[46:47], 0, s[74:75]
	v_lshl_add_u64 v[46:47], v[48:49], 0, s[74:75]
	v_lshl_add_u64 v[2:3], v[2:3], 0, v[4:5]
	v_lshl_add_u64 v[50:51], v[46:47], 0, v[4:5]
	global_load_dwordx2 v[48:49], v[2:3], off offset:64
	global_load_dwordx2 v[46:47], v[2:3], off
	s_nop 0
	global_load_dwordx2 v[52:53], v[50:51], off offset:64
	global_load_dwordx2 v[50:51], v[50:51], off
	v_lshlrev_b32_e32 v4, 1, v174
	v_lshl_add_u64 v[2:3], v[54:55], 0, v[4:5]
	v_lshl_add_u64 v[64:65], v[56:57], 0, v[4:5]
	s_add_i32 s78, s78, 0x1a000
	v_cmp_lt_u32_e64 s[12:13], v66, v67
	v_cmp_gt_u32_e64 s[6:7], 32, v20
	v_lshlrev_b32_e32 v173, 10, v21
	v_lshlrev_b32_e32 v188, 4, v175
	v_cndmask_b32_e64 v122, 0, v185, s[6:7]
	v_cndmask_b32_e64 v121, 0, -1.0, s[6:7]
	v_mov_b32_e32 v120, v5
	v_mov_b32_e32 v123, v5
	v_lshl_add_u32 v182, v175, 2, s78
	v_mov_b32_e32 v156, v5

; #define LAS __attribute__((address_space(3)))
; __device__ __forceinline__ unsigned cvtpk(float lo, float hi) { f32x2 v = {lo, hi}; bf16x2_t b = __builtin_convertvector(v, bf16x2_t); return __builtin_bit_cast(unsigned, b); }
; __device__ __forceinline__ float bf_hi_part(float x) { return __uint_as_float(cvtpk(x, 0.f) << 16); }
; __device__ __forceinline__ void prompt_unit_fox(const Args& a, int l, int b, int h, int qb, LAS unsigned char* lds) {
;     ...
;     { const int idx = tid * 4; if (idx < q0 + 256) { const f32x4 c = *(const f32x4*)((const float*)(a.ws + WS_CKP) + (size_t)(b * 8 + h) * T + idx); *(LAS f32x4*)(lds + F_CK + idx * 4) = c;
; #pragma unroll
;         for (int e = 0; e < 4; ++e) { const float h1 = bf_hi_part(c[e]), r1 = c[e] - h1, h2 = bf_hi_part(r1), r2 = r1 - h2; ((LAS u32x2*)(lds + F_AUG))[idx + e] = (u32x2){cvtpk(h1, h2), cvtpk(r2, -1.0f)}; } } }
	s_cmp_lg_u32 s83, 0
	s_cbranch_scc0 .Lck_skip_l0
	s_waitcnt vmcnt(20)
	ds_write_b128 v85, v[92:95]
	v_cvt_pk_bf16_f32 v85, v92, 0
	v_cvt_pk_bf16_f32 v87, v93, 0
	v_cvt_pk_bf16_f32 v88, v94, 0
	v_cvt_pk_bf16_f32 v91, v95, 0
	v_lshlrev_b32_e32 v85, 16, v85
	v_lshlrev_b32_e32 v87, 16, v87
	v_lshlrev_b32_e32 v88, 16, v88
	v_lshlrev_b32_e32 v91, 16, v91
	v_sub_f32_e32 v92, v92, v85
	v_sub_f32_e32 v93, v93, v87
	v_sub_f32_e32 v96, v94, v88
	v_sub_f32_e32 v95, v95, v91
	v_cvt_pk_bf16_f32 v94, v92, 0
	v_cvt_pk_bf16_f32 v97, v93, 0
	v_cvt_pk_bf16_f32 v98, v96, 0
	v_cvt_pk_bf16_f32 v99, v95, 0
	v_lshlrev_b32_e32 v94, 16, v94
	v_lshlrev_b32_e32 v97, 16, v97
	v_lshlrev_b32_e32 v98, 16, v98
	v_lshlrev_b32_e32 v99, 16, v99
	v_sub_f32_e32 v100, v92, v94
	v_cvt_pk_bf16_f32 v92, v85, v94
	v_sub_f32_e32 v85, v93, v97
	v_cvt_pk_bf16_f32 v94, v87, v97
	v_sub_f32_e32 v87, v96, v98
	v_cvt_pk_bf16_f32 v96, v88, v98
	v_sub_f32_e32 v88, v95, v99
	v_cvt_pk_bf16_f32 v93, v100, -1.0
	v_cvt_pk_bf16_f32 v95, v85, -1.0
	v_cvt_pk_bf16_f32 v98, v91, v99
	v_cvt_pk_bf16_f32 v97, v87, -1.0
	v_cvt_pk_bf16_f32 v99, v88, -1.0
	ds_write_b128 v86, v[92:95]
	ds_write_b128 v86, v[96:99] offset:16

; __device__ __forceinline__ void vfrags(VFrags& v, lds_cptr vp) {
; #pragma unroll
;     ...
; }
; __device__ __forceinline__ void pv(f32x16 (&o)[2], const VFrags& v, const u32x4& pw0, const u32x4& pw1, const u32x4& pw2, const u32x4& pw3) {
;     ...
;     o[0] = __builtin_amdgcn_mfma_f32_32x32x16_bf16(__builtin_bit_cast(bf16x8, pw0), ATT_VF(0), o[0], 0, 0, 0);
;     o[1] = __builtin_amdgcn_mfma_f32_32x32x16_bf16(__builtin_bit_cast(bf16x8, pw0), ATT_VF(4), o[1], 0, 0, 0);
;     o[0] = __builtin_amdgcn_mfma_f32_32x32x16_bf16(__builtin_bit_cast(bf16x8, pw1), ATT_VF(1), o[0], 0, 0, 0);
;     o[1] = __builtin_amdgcn_mfma_f32_32x32x16_bf16(__builtin_bit_cast(bf16x8, pw1), ATT_VF(5), o[1], 0, 0, 0);
;     o[0] = __builtin_amdgcn_mfma_f32_32x32x16_bf16(__builtin_bit_cast(bf16x8, pw2), ATT_VF(2), o[0], 0, 0, 0);
;     o[1] = __builtin_amdgcn_mfma_f32_32x32x16_bf16(__builtin_bit_cast(bf16x8, pw2), ATT_VF(6), o[1], 0, 0, 0);
;     o[0] = __builtin_amdgcn_mfma_f32_32x32x16_bf16(__builtin_bit_cast(bf16x8, pw3), ATT_VF(3), o[0], 0, 0, 0);
;     o[1] = __builtin_amdgcn_mfma_f32_32x32x16_bf16(__builtin_bit_cast(bf16x8, pw3), ATT_VF(7), o[1], 0, 0, 0);
;     ...
; }
; __device__ __forceinline__ void fox_pair_pv(FoxState& st, const PairP& pp, lds_cptr vpB) {
;     { VFrags vf; vfrags(vf, vpB + 8192); pv(st.o, vf, pp.w[0], pp.w[1], pp.w[2], pp.w[3]); }
;     { VFrags vf; vfrags(vf, vpB); pv(st.o, vf, pp.w[4], pp.w[5], pp.w[6], pp.w[7]); }
; }
.LBB0_348:
	s_setprio 0
	s_nop 11
	v_mov_b64_e32 v[68:69], v[20:21]
	v_mov_b64_e32 v[70:71], v[22:23]
	v_mov_b64_e32 v[72:73], v[24:25]
	v_mov_b64_e32 v[74:75], v[26:27]
	v_mov_b64_e32 v[76:77], v[28:29]
	v_mov_b64_e32 v[78:79], v[30:31]
	v_mov_b64_e32 v[80:81], v[32:33]
	v_mov_b64_e32 v[82:83], v[34:35]
	v_mov_b64_e32 v[52:53], v[36:37]
	v_mov_b64_e32 v[54:55], v[38:39]
	v_mov_b64_e32 v[56:57], v[40:41]
	v_mov_b64_e32 v[58:59], v[42:43]
	v_mov_b64_e32 v[60:61], v[44:45]
	v_mov_b64_e32 v[62:63], v[46:47]
	v_mov_b64_e32 v[64:65], v[48:49]
	v_mov_b64_e32 v[66:67], v[50:51]
	s_and_b64 vcc, exec, s[4:5]
	s_cbranch_vccz .LBB0_350
	v_lshl_add_u32 v2, s1, 14, v180
	ds_read_b64_tr_b16 v[6:7], v2 offset:57344
	ds_read_b64_tr_b16 v[8:9], v2 offset:57856
	ds_read_b64_tr_b16 v[10:11], v2 offset:58368
	ds_read_b64_tr_b16 v[12:13], v2 offset:58880
	s_waitcnt lgkmcnt(2)
	v_mfma_f32_32x32x16_bf16 v[68:83], v[152:155], v[6:9], v[68:83]
	ds_read_b64_tr_b16 v[6:7], v2 offset:61440
	ds_read_b64_tr_b16 v[8:9], v2 offset:61952
	ds_read_b64_tr_b16 v[14:15], v2 offset:62464
	ds_read_b64_tr_b16 v[16:17], v2 offset:62976
	s_waitcnt lgkmcnt(2)
	v_mfma_f32_32x32x16_bf16 v[52:67], v[152:155], v[6:9], v[52:67]
	v_mfma_f32_32x32x16_bf16 v[68:83], v[148:151], v[10:13], v[68:83]
	ds_read_b64_tr_b16 v[6:7], v2 offset:59392
	ds_read_b64_tr_b16 v[8:9], v2 offset:59904
	ds_read_b64_tr_b16 v[10:11], v2 offset:60416
	ds_read_b64_tr_b16 v[12:13], v2 offset:60928
	s_waitcnt lgkmcnt(4)
	v_mfma_f32_32x32x16_bf16 v[52:67], v[148:151], v[14:17], v[52:67]
	s_waitcnt lgkmcnt(2)
	v_mfma_f32_32x32x16_bf16 v[68:83], v[144:147], v[6:9], v[68:83]
	ds_read_b64_tr_b16 v[6:7], v2 offset:63488
	ds_read_b64_tr_b16 v[8:9], v2 offset:64000
	ds_read_b64_tr_b16 v[14:15], v2 offset:64512
	ds_read_b64_tr_b16 v[16:17], v2 offset:65024
	s_waitcnt lgkmcnt(2)
	v_mfma_f32_32x32x16_bf16 v[52:67], v[144:147], v[6:9], v[52:67]
	v_mfma_f32_32x32x16_bf16 v[68:83], v[140:143], v[10:13], v[68:83]
	ds_read_b64_tr_b16 v[6:7], v2 offset:49152
	ds_read_b64_tr_b16 v[8:9], v2 offset:49664
	ds_read_b64_tr_b16 v[10:11], v2 offset:50176
	ds_read_b64_tr_b16 v[12:13], v2 offset:50688
	s_waitcnt lgkmcnt(4)
	v_mfma_f32_32x32x16_bf16 v[52:67], v[140:143], v[14:17], v[52:67]
	s_waitcnt lgkmcnt(2)
	v_mfma_f32_32x32x16_bf16 v[68:83], v[136:139], v[6:9], v[68:83]
	ds_read_b64_tr_b16 v[6:7], v2 offset:53248
	ds_read_b64_tr_b16 v[8:9], v2 offset:53760
	ds_read_b64_tr_b16 v[14:15], v2 offset:54272
	ds_read_b64_tr_b16 v[16:17], v2 offset:54784
	s_waitcnt lgkmcnt(2)
	v_mfma_f32_32x32x16_bf16 v[52:67], v[136:139], v[6:9], v[52:67]
	v_mfma_f32_32x32x16_bf16 v[68:83], v[132:135], v[10:13], v[68:83]
	ds_read_b64_tr_b16 v[6:7], v2 offset:51200
	ds_read_b64_tr_b16 v[8:9], v2 offset:51712
	ds_read_b64_tr_b16 v[10:11], v2 offset:52224
	ds_read_b64_tr_b16 v[12:13], v2 offset:52736
	s_waitcnt lgkmcnt(4)
	v_mfma_f32_32x32x16_bf16 v[52:67], v[132:135], v[14:17], v[52:67]
	s_waitcnt lgkmcnt(2)
	v_mfma_f32_32x32x16_bf16 v[68:83], v[128:131], v[6:9], v[68:83]
	ds_read_b64_tr_b16 v[6:7], v2 offset:55296
	ds_read_b64_tr_b16 v[8:9], v2 offset:55808
	ds_read_b64_tr_b16 v[14:15], v2 offset:56320
	ds_read_b64_tr_b16 v[16:17], v2 offset:56832
	s_waitcnt lgkmcnt(2)
	v_mfma_f32_32x32x16_bf16 v[52:67], v[128:131], v[6:9], v[52:67]
	v_mfma_f32_32x32x16_bf16 v[68:83], v[124:127], v[10:13], v[68:83]
	s_waitcnt lgkmcnt(0)
	v_mfma_f32_32x32x16_bf16 v[52:67], v[124:127], v[14:17], v[52:67]

;     ...
;     if (masked) {
;         asm volatile("; masked tile" ::: "memory");
; #pragma unroll
;         for (int r = 0; r < 16; ++r) { const int kv = crow(r, hi); if (kv >= qlim) p0[r] = NEG; if (kv + 32 >= qlim) p1[r] = NEG; }
; __device__ __forceinline__ void prompt_unit_fox(const Args& a, int l, int b, int h, int qb, LAS unsigned char* lds) {
;     int tid_ = threadIdx.x; asm volatile("" : "+v"(tid_));
;     const int tid = tid_, lane = tid & 63, r32 = lane & 31, hi = lane >> 5, wid = __builtin_amdgcn_readfirstlane(tid >> 6);
;     const int q0 = qb * 256, NP = (q0 + 256) / 128, jd = q0 / 64 + (wid >> 1), jpd = jd >> 1;
;     const bool lateB = wid >= 4;
;     const int col = h * HD;
;     const size_t rowb = (size_t)b * T;
;     const bf16* Kh = (const bf16*)(a.ws + WS_K) + rowb * D + col; const bf16* Vh = (const bf16*)(a.ws + WS_V) + rowb * D + col;
;     const unsigned lds0 = (unsigned)(uintptr_t)lds;
;     const bf16* ksrc = Kh + (size_t)lane * D + wid * 8;
;     const bf16* vsrc = Vh + (size_t)(16 * (wid & 3) + (lane >> 2)) * D + (wid >> 2) * 32 + (lane & 3) * 8;
;     ...
;     ATT_DMA2(NP - 1, 0);
;     { const int idx = tid * 4; if (idx < q0 + 256) { const f32x4 c = *(const f32x4*)((const float*)(a.ws + WS_CKP) + (size_t)(b * 8 + h) * T + idx); *(LAS f32x4*)(lds + F_CK + idx * 4) = c;
; #pragma unroll
;         for (int e = 0; e < 4; ++e) { const float h1 = bf_hi_part(c[e]), r1 = c[e] - h1, h2 = bf_hi_part(r1), r2 = r1 - h2; ((LAS u32x2*)(lds + F_AUG))[idx + e] = (u32x2){cvtpk(h1, h2), cvtpk(r2, -1.0f)}; } } }
;     bf16x8 qr[4];
;     { const bf16* Qw = (const bf16*)(a.ws + WS_Q) + (rowb + q0 + wid * 32 + r32) * D + col;
; #pragma unroll
;       for (int d0 = 0; d0 < 4; ++d0) qr[d0] = *(const bf16x8*)(Qw + d0 * 16 + hi * 8); }
;     const lds_cptr vp0 = (lds_cptr)lds + F_V + ((lane >> 4) & 1) * 32 + (lane & 3) * 8 + (4 * hi + ((lane & 15) >> 2)) * 64;
;     const int ql = 32 * (wid & 1) + r32, qlim = ql + 1;
;     LAS float* wsf = (LAS float*)(lds + F_WSF) + wid * 64;
;     FoxState st; st.m = 0.f; st.l = 0.f; st.mq = (bf16x8){}; st.o[0] = (f32x16){}; st.o[1] = (f32x16){};
;     PairP pp; bool pending = false;
; #pragma unroll
;     for (int i = 0; i < 8; ++i) pp.w[i] = (u32x4){0u, 0u, 0u, 0u};
;     { ConvRegs cv; conv_load(cv, a, rowb + q0 + wid * 32, col, lane); conv_store<0>(cv, a, l, h, rowb + q0 + wid * 32, lane); }
.LBB0_963:
	v_writelane_b32 v242, s16, 32
	s_or_b64 exec, exec, s[2:3]
	s_lshl_b32 s0, s0, 2
	s_ashr_i32 s2, s6, 7
	s_add_i32 s2, s2, s0
	s_ashr_i32 s0, s2, 1
	s_cmp_lt_i32 s1, 4
	s_cselect_b64 s[90:91], -1, 0
	s_cbranch_scc1 .Lnoprio_l1
	s_setprio 1
.Lnoprio_l1:
	s_lshl_b32 s2, s8, 11
	s_lshl_b32 s3, s1, 5
	s_or_b32 s2, s9, s2
	s_ashr_i32 s8, s3, 31
	s_add_u32 s79, s3, s2
	v_and_b32_e32 v180, 31, v19
	s_addc_u32 s10, s8, 0
	v_or_b32_e32 v168, s79, v180
	v_mov_b32_e32 v169, s10
	v_readlane_b32 s8, v242, 28
	v_lshlrev_b64 v[2:3], 11, v[168:169]
	v_readlane_b32 s9, v242, 29
	v_lshrrev_b32_e32 v21, 5, v20
	s_lshl_b32 s74, s7, 1
	v_lshl_add_u64 v[2:3], s[8:9], 0, v[2:3]
	s_mov_b32 s75, s87
	v_lshl_add_u64 v[2:3], v[2:3], 0, s[74:75]
	v_lshlrev_b32_e32 v174, 4, v21
	v_mov_b32_e32 v175, v5
	v_lshl_add_u64 v[2:3], v[2:3], 0, v[174:175]
	global_load_dwordx4 v[6:9], v[2:3], off
	global_load_dwordx4 v[10:13], v[2:3], off offset:32
	global_load_dwordx4 v[14:17], v[2:3], off offset:64
	global_load_dwordx4 v[116:119], v[2:3], off offset:96
	v_lshlrev_b32_e32 v2, 1, v19
	v_and_b32_e32 v2, 32, v2
	v_add_u32_e32 v3, 0, v2
	v_lshlrev_b32_e32 v2, 2, v21
	v_lshrrev_b32_e32 v4, 2, v19
	v_and_or_b32 v4, v4, 3, v2
	v_lshlrev_b32_e32 v4, 6, v4
	s_and_b32 s2, s6, 0x3fffffc0
	v_add3_u32 v175, v3, v1, v4
	s_lshl_b32 s2, s2, 2
	v_lshrrev_b32_e32 v1, 3, v20
	v_and_or_b32 v3, s3, 32, v180
	s_add_i32 s89, s2, 0
	v_or_b32_e32 v168, s79, v1
	v_readlane_b32 s2, v242, 20
	v_lshlrev_b32_e32 v4, 3, v20
	v_lshlrev_b64 v[176:177], 11, v[168:169]
	v_readlane_b32 s3, v242, 21
	v_readlane_b32 s8, v242, 22
	v_and_b32_e32 v178, 56, v4
	v_lshl_add_u64 v[22:23], s[2:3], 0, v[176:177]
	v_readlane_b32 s9, v242, 23
	v_lshl_add_u64 v[22:23], v[22:23], 0, s[74:75]
	v_mov_b32_e32 v4, v178
	v_lshl_add_u64 v[26:27], s[8:9], 0, v[176:177]
	v_lshl_add_u64 v[22:23], v[22:23], 0, v[4:5]
	v_lshl_add_u64 v[26:27], v[26:27], 0, s[74:75]
	v_or_b32_e32 v34, 0x4000, v176
	v_mov_b32_e32 v35, v177
	global_load_dwordx2 v[24:25], v[22:23], off offset:64
	global_load_dwordx2 v[22:23], v[22:23], off
	v_lshl_add_u64 v[26:27], v[26:27], 0, v[4:5]
	v_lshl_add_u64 v[30:31], s[2:3], 0, v[34:35]
	global_load_dwordx2 v[28:29], v[26:27], off offset:64
	global_load_dwordx2 v[26:27], v[26:27], off
	v_lshl_add_u64 v[30:31], v[30:31], 0, s[74:75]
	v_lshl_add_u64 v[30:31], v[30:31], 0, v[4:5]
	global_load_dwordx2 v[32:33], v[30:31], off offset:64
	global_load_dwordx2 v[30:31], v[30:31], off
	v_lshl_add_u64 v[34:35], s[8:9], 0, v[34:35]
	v_lshl_add_u64 v[34:35], v[34:35], 0, s[74:75]
	v_lshl_add_u64 v[34:35], v[34:35], 0, v[4:5]
	global_load_dwordx2 v[36:37], v[34:35], off offset:64
	global_load_dwordx2 v[34:35], v[34:35], off
	v_or_b32_e32 v42, 0x8000, v176
	v_mov_b32_e32 v43, v177
	v_lshl_add_u64 v[38:39], s[2:3], 0, v[42:43]
	v_lshl_add_u64 v[38:39], v[38:39], 0, s[74:75]
	v_lshl_add_u64 v[38:39], v[38:39], 0, v[4:5]
	global_load_dwordx2 v[40:41], v[38:39], off offset:64
	global_load_dwordx2 v[38:39], v[38:39], off
	v_lshl_add_u64 v[42:43], s[8:9], 0, v[42:43]
	v_lshl_add_u64 v[42:43], v[42:43], 0, s[74:75]
	v_lshl_add_u64 v[42:43], v[42:43], 0, v[4:5]
	global_load_dwordx2 v[44:45], v[42:43], off offset:64
	global_load_dwordx2 v[42:43], v[42:43], off
	v_or_b32_e32 v50, 0xc000, v176
	v_mov_b32_e32 v51, v177
	v_lshl_add_u64 v[46:47], s[2:3], 0, v[50:51]
	v_lshl_add_u64 v[46:47], v[46:47], 0, s[74:75]
	v_lshl_add_u64 v[46:47], v[46:47], 0, v[4:5]
	global_load_dwordx2 v[48:49], v[46:47], off offset:64
	global_load_dwordx2 v[46:47], v[46:47], off
	v_lshl_add_u64 v[50:51], s[8:9], 0, v[50:51]
	v_lshl_add_u64 v[50:51], v[50:51], 0, s[74:75]
	v_lshl_add_u64 v[50:51], v[50:51], 0, v[4:5]
	global_load_dwordx2 v[52:53], v[50:51], off offset:64
	global_load_dwordx2 v[50:51], v[50:51], off
	s_add_i32 s89, s89, 0x1a000
	s_add_u32 s2, s79, 0x10000
	v_writelane_b32 v242, s10, 34
	s_addc_u32 s3, s10, 0
	v_or_b32_e32 v54, s2, v1
	v_mov_b32_e32 v55, s3
	v_readlane_b32 s2, v242, 26
	v_lshlrev_b64 v[54:55], 11, v[54:55]
	v_readlane_b32 s3, v242, 27
	s_lshl_b32 s92, s7, 2
	s_mov_b32 s93, s87
	v_lshl_add_u64 v[56:57], s[2:3], 0, v[54:55]
	v_readlane_b32 s2, v242, 43
	v_readlane_b32 s3, v242, 44
	v_lshl_add_u64 v[56:57], v[56:57], 0, s[92:93]
	v_lshlrev_b32_e32 v4, 1, v178
	v_lshl_add_u64 v[54:55], s[2:3], 0, v[54:55]
	v_lshl_add_u64 v[54:55], v[54:55], 0, s[92:93]
	v_lshl_add_u64 v[58:59], v[56:57], 0, v[4:5]
	v_lshl_add_u64 v[60:61], v[54:55], 0, v[4:5]
	v_or_b32_e32 v4, 32, v2
	v_cmp_gt_u32_e64 s[10:11], v4, v3
	v_or_b32_e32 v4, 33, v2
	v_cmp_gt_u32_e64 s[14:15], v4, v3
	v_or_b32_e32 v4, 2, v2
	v_cmp_gt_u32_e64 s[16:17], v4, v3
	v_or_b32_e32 v4, 34, v2
	v_cmp_gt_u32_e64 s[18:19], v4, v3
	v_or_b32_e32 v4, 3, v2
	v_cmp_gt_u32_e64 s[20:21], v4, v3
	v_or_b32_e32 v4, 35, v2
	v_cmp_gt_u32_e64 s[22:23], v4, v3
	v_or_b32_e32 v4, 8, v2
	s_mov_b64 s[2:3], 0x4000
	v_cmp_gt_u32_e64 s[24:25], v4, v3
	v_or_b32_e32 v4, 40, v2
	v_cmp_gt_u32_e64 s[26:27], v4, v3
	v_or_b32_e32 v4, 9, v2
	v_cmp_gt_u32_e64 s[28:29], v4, v3
	v_or_b32_e32 v4, 41, v2
	v_cmp_gt_u32_e64 s[30:31], v4, v3
	v_or_b32_e32 v4, 10, v2
	v_cmp_gt_u32_e64 s[34:35], v4, v3
	v_or_b32_e32 v4, 42, v2
	v_cmp_gt_u32_e64 s[36:37], v4, v3
	v_or_b32_e32 v4, 11, v2
	v_cmp_gt_u32_e64 s[38:39], v4, v3
	v_or_b32_e32 v4, 43, v2
	v_cmp_gt_u32_e64 s[40:41], v4, v3

; #define LAS __attribute__((address_space(3)))
; __device__ __forceinline__ unsigned cvtpk(float lo, float hi) { f32x2 v = {lo, hi}; bf16x2_t b = __builtin_convertvector(v, bf16x2_t); return __builtin_bit_cast(unsigned, b); }
; __device__ __forceinline__ float bf_hi_part(float x) { return __uint_as_float(cvtpk(x, 0.f) << 16); }
; __device__ __forceinline__ void prompt_unit_fox(const Args& a, int l, int b, int h, int qb, LAS unsigned char* lds) {
;     ...
;     { const int idx = tid * 4; if (idx < q0 + 256) { const f32x4 c = *(const f32x4*)((const float*)(a.ws + WS_CKP) + (size_t)(b * 8 + h) * T + idx); *(LAS f32x4*)(lds + F_CK + idx * 4) = c;
; #pragma unroll
;         for (int e = 0; e < 4; ++e) { const float h1 = bf_hi_part(c[e]), r1 = c[e] - h1, h2 = bf_hi_part(r1), r2 = r1 - h2; ((LAS u32x2*)(lds + F_AUG))[idx + e] = (u32x2){cvtpk(h1, h2), cvtpk(r2, -1.0f)}; } } }
	s_cmp_lg_u32 s83, 0
	s_cbranch_scc0 .Lck_skip_l1
	s_waitcnt vmcnt(20)
	ds_write_b128 v87, v[90:93]
	v_cvt_pk_bf16_f32 v87, v90, 0
	v_lshlrev_b32_e32 v87, 16, v87
	v_sub_f32_e32 v88, v90, v87
	v_cvt_pk_bf16_f32 v90, v88, 0
	v_lshlrev_b32_e32 v90, 16, v90
	v_cvt_pk_bf16_f32 v94, v87, v90
	v_cvt_pk_bf16_f32 v87, v91, 0
	v_sub_f32_e32 v88, v88, v90
	v_lshlrev_b32_e32 v87, 16, v87
	v_cvt_pk_bf16_f32 v95, v88, -1.0
	v_sub_f32_e32 v88, v91, v87
	v_cvt_pk_bf16_f32 v90, v88, 0
	v_lshlrev_b32_e32 v90, 16, v90
	v_cvt_pk_bf16_f32 v96, v87, v90
	v_cvt_pk_bf16_f32 v87, v92, 0
	v_sub_f32_e32 v88, v88, v90
	v_lshlrev_b32_e32 v87, 16, v87
	v_cvt_pk_bf16_f32 v97, v88, -1.0
	v_sub_f32_e32 v88, v92, v87
	v_cvt_pk_bf16_f32 v90, v88, 0
	v_lshlrev_b32_e32 v90, 16, v90
	v_sub_f32_e32 v88, v88, v90
	v_cvt_pk_bf16_f32 v90, v87, v90
	v_cvt_pk_bf16_f32 v87, v93, 0
	v_lshlrev_b32_e32 v87, 16, v87
	v_cvt_pk_bf16_f32 v91, v88, -1.0
	v_sub_f32_e32 v88, v93, v87
	v_cvt_pk_bf16_f32 v92, v88, 0
	v_lshlrev_b32_e32 v92, 16, v92
	v_sub_f32_e32 v88, v88, v92
	v_cvt_pk_bf16_f32 v92, v87, v92
	v_cvt_pk_bf16_f32 v93, v88, -1.0
	ds_write_b128 v86, v[94:97]
	ds_write_b128 v86, v[90:93] offset:16

; __device__ __forceinline__ void vfrags(VFrags& v, lds_cptr vp) {
; #pragma unroll
;     ...
; }
; __device__ __forceinline__ void pv(f32x16 (&o)[2], const VFrags& v, const u32x4& pw0, const u32x4& pw1, const u32x4& pw2, const u32x4& pw3) {
;     ...
;     o[0] = __builtin_amdgcn_mfma_f32_32x32x16_bf16(__builtin_bit_cast(bf16x8, pw0), ATT_VF(0), o[0], 0, 0, 0);
;     o[1] = __builtin_amdgcn_mfma_f32_32x32x16_bf16(__builtin_bit_cast(bf16x8, pw0), ATT_VF(4), o[1], 0, 0, 0);
;     o[0] = __builtin_amdgcn_mfma_f32_32x32x16_bf16(__builtin_bit_cast(bf16x8, pw1), ATT_VF(1), o[0], 0, 0, 0);
;     o[1] = __builtin_amdgcn_mfma_f32_32x32x16_bf16(__builtin_bit_cast(bf16x8, pw1), ATT_VF(5), o[1], 0, 0, 0);
;     o[0] = __builtin_amdgcn_mfma_f32_32x32x16_bf16(__builtin_bit_cast(bf16x8, pw2), ATT_VF(2), o[0], 0, 0, 0);
;     o[1] = __builtin_amdgcn_mfma_f32_32x32x16_bf16(__builtin_bit_cast(bf16x8, pw2), ATT_VF(6), o[1], 0, 0, 0);
;     o[0] = __builtin_amdgcn_mfma_f32_32x32x16_bf16(__builtin_bit_cast(bf16x8, pw3), ATT_VF(3), o[0], 0, 0, 0);
;     o[1] = __builtin_amdgcn_mfma_f32_32x32x16_bf16(__builtin_bit_cast(bf16x8, pw3), ATT_VF(7), o[1], 0, 0, 0);
;     ...
; }
; __device__ __forceinline__ void fox_pair_pv(FoxState& st, const PairP& pp, lds_cptr vpB) {
;     { VFrags vf; vfrags(vf, vpB + 8192); pv(st.o, vf, pp.w[0], pp.w[1], pp.w[2], pp.w[3]); }
;     { VFrags vf; vfrags(vf, vpB); pv(st.o, vf, pp.w[4], pp.w[5], pp.w[6], pp.w[7]); }
; }
.LBB0_1010:
	s_setprio 0
	s_nop 11
	v_mov_b64_e32 v[68:69], v[20:21]
	v_mov_b64_e32 v[70:71], v[22:23]
	v_mov_b64_e32 v[72:73], v[24:25]
	v_mov_b64_e32 v[74:75], v[26:27]
	v_mov_b64_e32 v[76:77], v[28:29]
	v_mov_b64_e32 v[78:79], v[30:31]
	v_mov_b64_e32 v[80:81], v[32:33]
	v_mov_b64_e32 v[82:83], v[34:35]
	v_mov_b64_e32 v[52:53], v[36:37]
	v_mov_b64_e32 v[54:55], v[38:39]
	v_mov_b64_e32 v[56:57], v[40:41]
	v_mov_b64_e32 v[58:59], v[42:43]
	v_mov_b64_e32 v[60:61], v[44:45]
	v_mov_b64_e32 v[62:63], v[46:47]
	v_mov_b64_e32 v[64:65], v[48:49]
	v_mov_b64_e32 v[66:67], v[50:51]
	s_and_b64 vcc, exec, s[2:3]
	s_cbranch_vccz .LBB0_1012
	v_lshl_add_u32 v2, s75, 14, v175
	ds_read_b64_tr_b16 v[6:7], v2 offset:57344
	ds_read_b64_tr_b16 v[8:9], v2 offset:57856
	ds_read_b64_tr_b16 v[10:11], v2 offset:58368
	ds_read_b64_tr_b16 v[12:13], v2 offset:58880
	s_waitcnt lgkmcnt(2)
	v_mfma_f32_32x32x16_bf16 v[68:83], v[152:155], v[6:9], v[68:83]
	ds_read_b64_tr_b16 v[6:7], v2 offset:61440
	ds_read_b64_tr_b16 v[8:9], v2 offset:61952
	ds_read_b64_tr_b16 v[14:15], v2 offset:62464
	ds_read_b64_tr_b16 v[16:17], v2 offset:62976
	s_waitcnt lgkmcnt(2)
	v_mfma_f32_32x32x16_bf16 v[52:67], v[152:155], v[6:9], v[52:67]
	v_mfma_f32_32x32x16_bf16 v[68:83], v[148:151], v[10:13], v[68:83]
	ds_read_b64_tr_b16 v[6:7], v2 offset:59392
	ds_read_b64_tr_b16 v[8:9], v2 offset:59904
	ds_read_b64_tr_b16 v[10:11], v2 offset:60416
	ds_read_b64_tr_b16 v[12:13], v2 offset:60928
	s_waitcnt lgkmcnt(4)
	v_mfma_f32_32x32x16_bf16 v[52:67], v[148:151], v[14:17], v[52:67]
	s_waitcnt lgkmcnt(2)
	v_mfma_f32_32x32x16_bf16 v[68:83], v[144:147], v[6:9], v[68:83]
	ds_read_b64_tr_b16 v[6:7], v2 offset:63488
	ds_read_b64_tr_b16 v[8:9], v2 offset:64000
	ds_read_b64_tr_b16 v[14:15], v2 offset:64512
	ds_read_b64_tr_b16 v[16:17], v2 offset:65024
	s_waitcnt lgkmcnt(2)
	v_mfma_f32_32x32x16_bf16 v[52:67], v[144:147], v[6:9], v[52:67]
	v_mfma_f32_32x32x16_bf16 v[68:83], v[140:143], v[10:13], v[68:83]
	ds_read_b64_tr_b16 v[6:7], v2 offset:49152
	ds_read_b64_tr_b16 v[8:9], v2 offset:49664
	ds_read_b64_tr_b16 v[10:11], v2 offset:50176
	ds_read_b64_tr_b16 v[12:13], v2 offset:50688
	s_waitcnt lgkmcnt(4)
	v_mfma_f32_32x32x16_bf16 v[52:67], v[140:143], v[14:17], v[52:67]
	s_waitcnt lgkmcnt(2)
	v_mfma_f32_32x32x16_bf16 v[68:83], v[136:139], v[6:9], v[68:83]
	ds_read_b64_tr_b16 v[6:7], v2 offset:53248
	ds_read_b64_tr_b16 v[8:9], v2 offset:53760
	ds_read_b64_tr_b16 v[14:15], v2 offset:54272
	ds_read_b64_tr_b16 v[16:17], v2 offset:54784
	s_waitcnt lgkmcnt(2)
	v_mfma_f32_32x32x16_bf16 v[52:67], v[136:139], v[6:9], v[52:67]
	v_mfma_f32_32x32x16_bf16 v[68:83], v[132:135], v[10:13], v[68:83]
	ds_read_b64_tr_b16 v[6:7], v2 offset:51200
	ds_read_b64_tr_b16 v[8:9], v2 offset:51712
	ds_read_b64_tr_b16 v[10:11], v2 offset:52224
	ds_read_b64_tr_b16 v[12:13], v2 offset:52736
	s_waitcnt lgkmcnt(4)
	v_mfma_f32_32x32x16_bf16 v[52:67], v[132:135], v[14:17], v[52:67]
	s_waitcnt lgkmcnt(2)
	v_mfma_f32_32x32x16_bf16 v[68:83], v[128:131], v[6:9], v[68:83]
	ds_read_b64_tr_b16 v[6:7], v2 offset:55296
	ds_read_b64_tr_b16 v[8:9], v2 offset:55808
	ds_read_b64_tr_b16 v[14:15], v2 offset:56320
	ds_read_b64_tr_b16 v[16:17], v2 offset:56832
	s_waitcnt lgkmcnt(2)
	v_mfma_f32_32x32x16_bf16 v[52:67], v[128:131], v[6:9], v[52:67]
	v_mfma_f32_32x32x16_bf16 v[68:83], v[124:127], v[10:13], v[68:83]
	s_waitcnt lgkmcnt(0)
	v_mfma_f32_32x32x16_bf16 v[52:67], v[124:127], v[14:17], v[52:67]
